# combo9 + E37/E38: phase 1 produces u for slabs 0 and 3; slabs 1 and 2 are produced inside slab 0's in-proj phase (whose idle CUs have no deferred PG to run), pipelined row loop
# speedup vs baseline: 1.0024x; 1.0024x over previous
.LBB0_11:
	s_mov_b64 s[10:11], -1
	s_mov_b64 s[0:1], 0
	s_cmp_lt_i32 s6, 1
	s_mov_b64 s[8:9], 0
	s_mov_b64 s[12:13], 0
	s_cbranch_scc1 .LBB0_17
	s_mov_b64 s[12:13], -1
	s_mov_b64 s[10:11], 0
	s_cmp_eq_u32 s6, 1
	s_cbranch_scc0 .LBB0_17
	v_mov_b32_e32 v0, v167
	v_readlane_b32 s9, v251, 14
	v_readfirstlane_b32 s8, v0
	s_ashr_i32 s8, s8, 6
	s_add_i32 s8, s8, s9
	s_mov_b32 s3, 0
	s_cmpk_lg_u32 s36, 0x100
	s_cbranch_scc1 .Lp1_bnd
	s_movk_i32 s3, 0x4000
.Lp1_bnd:
	s_cmpk_gt_i32 s8, 0x7fff
	s_cbranch_scc1 .LBB0_16
	v_cmp_lt_i32_e32 vcc, v188, v187
	v_and_b32_e32 v4, 63, v0
	v_readlane_b32 s84, v254, 4
	v_cndmask_b32_e32 v2, v185, v188, vcc
	v_cmp_lt_i32_e32 vcc, v189, v187
	v_lshlrev_b32_e32 v6, 2, v2
	v_lshlrev_b32_e32 v156, 4, v4
	v_cndmask_b32_e32 v2, v185, v189, vcc
	v_cmp_lt_i32_e32 vcc, v190, v187
	v_lshlrev_b32_e32 v7, 2, v2
	v_readlane_b32 s85, v254, 5
	v_cndmask_b32_e32 v2, v185, v190, vcc
	v_cmp_lt_i32_e32 vcc, v191, v187
	s_waitcnt vmcnt(0)
	v_lshlrev_b32_e32 v8, 2, v2
	v_readlane_b32 s88, v254, 8
	v_cndmask_b32_e32 v2, v185, v191, vcc
	v_cmp_lt_i32_e32 vcc, v250, v187
	v_lshlrev_b32_e32 v9, 2, v2
	v_readlane_b32 s89, v254, 9
	v_cndmask_b32_e32 v2, v185, v250, vcc
	v_cmp_lt_i32_e32 vcc, v184, v187
	v_lshlrev_b32_e32 v10, 2, v2
	v_lshlrev_b32_e32 v12, 2, v4
	v_cndmask_b32_e32 v2, v185, v184, vcc
	v_readlane_b32 s12, v251, 12
	s_waitcnt lgkmcnt(0)
	v_lshl_add_u64 v[0:1], s[84:85], 0, v[156:157]
	v_lshlrev_b32_e32 v11, 2, v2
	v_lshl_add_u64 v[2:3], s[88:89], 0, v[156:157]
	v_or_b32_e32 v14, 0x100, v12
	v_or_b32_e32 v16, 0x200, v12
	v_or_b32_e32 v18, 0x300, v12
	v_lshlrev_b32_e32 v156, 3, v4
	v_readlane_b32 s13, v251, 13
	v_lshlrev_b32_e32 v12, 2, v12
	v_lshlrev_b32_e32 v13, 2, v14
	v_lshl_add_u64 v[4:5], s[12:13], 0, v[156:157]
	v_lshlrev_b32_e32 v14, 2, v16
	v_lshlrev_b32_e32 v15, 2, v18
	v_readlane_b32 s86, v254, 6
	v_readlane_b32 s87, v254, 7
	v_readlane_b32 s90, v254, 10
	v_readlane_b32 s91, v254, 11
	v_readlane_b32 s92, v254, 12
	v_readlane_b32 s93, v254, 13
	v_readlane_b32 s94, v254, 14
	v_readlane_b32 s95, v254, 15
	v_readlane_b32 s96, v254, 16
	v_readlane_b32 s97, v254, 17
	v_readlane_b32 s98, v254, 18
	v_readlane_b32 s99, v254, 19
.LBB0_15:
	s_ashr_i32 s9, s8, 31
	s_lshl_b64 s[12:13], s[8:9], 12
	v_lshl_add_u64 v[28:29], v[0:1], 0, s[12:13]
	global_load_dwordx4 v[16:19], v[28:29], off
	global_load_dwordx4 v[20:23], v[28:29], off offset:1024
	global_load_dwordx4 v[24:27], v[28:29], off offset:2048
	s_nop 0
	global_load_dwordx4 v[28:31], v[28:29], off offset:3072
	s_lshr_b32 s12, s9, 19
	s_add_i32 s12, s8, s12
	s_ashr_i32 s12, s12, 13
	s_mulk_i32 s12, 0xc00
	s_ashr_i32 s13, s12, 31
	s_lshl_b64 s[12:13], s[12:13], 2
	s_add_u32 s12, s58, s12
	s_addc_u32 s13, s59, s13
	s_add_u32 s14, s12, 0x1000
	s_addc_u32 s15, s13, 0
	global_load_dwordx4 v[32:35], v12, s[14:15]
	global_load_dwordx4 v[36:39], v[2:3], off
	global_load_dwordx4 v[40:43], v12, s[12:13]
	s_lshl_b64 s[16:17], s[8:9], 11
	s_add_i32 s8, s8, s33
	s_cmpk_lt_i32 s8, 0x2000
	s_cbranch_scc1 .Lp1_nj
	s_cmpk_gt_i32 s8, 0x5fff
	s_cbranch_scc1 .Lp1_nj
	s_add_i32 s8, s8, s3
.Lp1_nj:
	s_cmpk_gt_i32 s8, 0x7fff
	s_waitcnt vmcnt(6)
	v_mov_b32_e32 v46, v17
	s_waitcnt vmcnt(5)
	v_mov_b32_e32 v47, v21
	v_mov_b32_e32 v44, v16
	v_mov_b32_e32 v45, v20
	s_waitcnt vmcnt(4)
	v_mov_b32_e32 v54, v25
	s_waitcnt vmcnt(3)
	v_mov_b32_e32 v55, v29
	v_pk_mul_f32 v[46:47], v[46:47], v[46:47]
	v_mov_b32_e32 v48, v18
	v_mov_b32_e32 v49, v22
	v_mov_b32_e32 v52, v24
	v_mov_b32_e32 v53, v28
	v_pk_mul_f32 v[54:55], v[54:55], v[54:55]
	v_pk_fma_f32 v[44:45], v[44:45], v[44:45], v[46:47]
	v_mov_b32_e32 v50, v19
	v_mov_b32_e32 v51, v23
	v_mov_b32_e32 v56, v26
	v_mov_b32_e32 v57, v30
	v_pk_fma_f32 v[46:47], v[52:53], v[52:53], v[54:55]
	v_pk_fma_f32 v[44:45], v[48:49], v[48:49], v[44:45]
	v_mov_b32_e32 v58, v27
	v_mov_b32_e32 v59, v31
	v_pk_fma_f32 v[46:47], v[56:57], v[56:57], v[46:47]
	v_pk_fma_f32 v[44:45], v[50:51], v[50:51], v[44:45]
	v_pk_fma_f32 v[46:47], v[58:59], v[58:59], v[46:47]
	v_add_f32_e32 v44, v44, v45
	v_add_f32_e32 v44, v44, v46
	v_add_f32_e32 v44, v44, v47
	ds_bpermute_b32 v45, v6, v44
	s_waitcnt vmcnt(2)
	v_add_f32_e32 v32, 1.0, v32
	v_add_f32_e32 v33, 1.0, v33
	v_add_f32_e32 v34, 1.0, v34
	v_add_f32_e32 v35, 1.0, v35
	s_waitcnt lgkmcnt(0)
	v_add_f32_e32 v44, v44, v45
	ds_bpermute_b32 v45, v7, v44
	s_waitcnt lgkmcnt(0)
	v_add_f32_e32 v44, v44, v45
	ds_bpermute_b32 v45, v8, v44
	s_waitcnt lgkmcnt(0)
	v_add_f32_e32 v44, v44, v45
	ds_bpermute_b32 v45, v9, v44
	s_waitcnt lgkmcnt(0)
	v_add_f32_e32 v44, v44, v45
	ds_bpermute_b32 v45, v10, v44
	s_waitcnt lgkmcnt(0)
	v_add_f32_e32 v46, v44, v45
	ds_bpermute_b32 v47, v11, v46
	v_lshl_add_u64 v[44:45], v[4:5], 0, s[16:17]
	s_waitcnt lgkmcnt(0)
	v_add_f32_e32 v46, v46, v47
	v_fmamk_f32 v46, v46, 0x3a800000, v182
	v_mul_f32_e32 v47, 0x4b800000, v46
	v_cmp_gt_f32_e32 vcc, s56, v46
	s_nop 1
	v_cndmask_b32_e32 v46, v46, v47, vcc
	v_rsq_f32_e32 v46, v46
	s_nop 0
	v_mul_f32_e32 v47, 0x45800000, v46
	v_cndmask_b32_e32 v46, v46, v47, vcc
	v_mul_f32_e32 v16, v16, v46
	v_mul_f32_e32 v17, v17, v46
	v_mul_f32_e32 v18, v18, v46
	v_mul_f32_e32 v19, v19, v46
	s_waitcnt vmcnt(1)
	v_mul_f32_e32 v16, v36, v16
	v_mul_f32_e32 v17, v37, v17
	v_mul_f32_e32 v18, v38, v18
	v_mul_f32_e32 v19, v39, v19
	s_waitcnt vmcnt(0)
	v_fma_f32 v16, v32, v16, v40
	v_fma_f32 v17, v33, v17, v41
	v_fma_f32 v18, v34, v18, v42
	v_fmac_f32_e32 v43, v19, v35
	v_cvt_pk_bf16_f32 v16, v16, v17
	v_cvt_pk_bf16_f32 v17, v18, v43
	global_store_dwordx2 v[44:45], v[16:17], off
	global_load_dwordx4 v[16:19], v[2:3], off offset:1024
	s_nop 0
	global_load_dwordx4 v[32:35], v13, s[14:15]
	global_load_dwordx4 v[36:39], v12, s[12:13] offset:1024
	v_mul_f32_e32 v20, v20, v46
	v_mul_f32_e32 v21, v21, v46
	v_mul_f32_e32 v22, v22, v46
	v_mul_f32_e32 v23, v23, v46
	v_mul_f32_e32 v24, v24, v46
	v_mul_f32_e32 v25, v25, v46
	v_mul_f32_e32 v26, v26, v46
	v_mul_f32_e32 v27, v27, v46
	v_mul_f32_e32 v28, v28, v46
	v_mul_f32_e32 v29, v29, v46
	v_mul_f32_e32 v30, v30, v46
	v_mul_f32_e32 v31, v31, v46
	s_waitcnt vmcnt(2)
	v_mul_f32_e32 v16, v20, v16
	s_waitcnt vmcnt(1)
	v_add_f32_e32 v20, 1.0, v32
	v_mul_f32_e32 v17, v21, v17
	v_add_f32_e32 v21, 1.0, v33
	v_mul_f32_e32 v18, v22, v18
	v_add_f32_e32 v22, 1.0, v34
	v_mul_f32_e32 v19, v23, v19
	v_add_f32_e32 v23, 1.0, v35
	s_waitcnt vmcnt(0)
	v_fma_f32 v16, v16, v20, v36
	v_fma_f32 v17, v17, v21, v37
	v_fma_f32 v18, v18, v22, v38
	v_fmac_f32_e32 v39, v19, v23
	v_cvt_pk_bf16_f32 v16, v16, v17
	v_cvt_pk_bf16_f32 v17, v18, v39
	global_store_dwordx2 v[44:45], v[16:17], off offset:512
	global_load_dwordx4 v[16:19], v[2:3], off offset:2048
	s_nop 0
	global_load_dwordx4 v[20:23], v14, s[14:15]
	global_load_dwordx4 v[32:35], v12, s[12:13] offset:2048
	s_waitcnt vmcnt(2)
	v_mul_f32_e32 v16, v24, v16
	s_waitcnt vmcnt(1)
	v_add_f32_e32 v20, 1.0, v20
	v_mul_f32_e32 v17, v25, v17
	v_add_f32_e32 v21, 1.0, v21
	v_mul_f32_e32 v18, v26, v18
	v_add_f32_e32 v22, 1.0, v22
	v_mul_f32_e32 v19, v27, v19
	v_add_f32_e32 v23, 1.0, v23
	s_waitcnt vmcnt(0)
	v_fma_f32 v16, v16, v20, v32
	v_fma_f32 v17, v17, v21, v33
	v_fma_f32 v18, v18, v22, v34
	v_fmac_f32_e32 v35, v19, v23
	v_cvt_pk_bf16_f32 v16, v16, v17
	v_cvt_pk_bf16_f32 v17, v18, v35
	global_store_dwordx2 v[44:45], v[16:17], off offset:1024
	global_load_dwordx4 v[16:19], v[2:3], off offset:3072
	s_nop 0
	global_load_dwordx4 v[20:23], v15, s[14:15]
	global_load_dwordx4 v[24:27], v12, s[12:13] offset:3072
	s_waitcnt vmcnt(2)
	v_mul_f32_e32 v16, v28, v16
	s_waitcnt vmcnt(1)
	v_add_f32_e32 v20, 1.0, v20
	v_mul_f32_e32 v17, v29, v17
	v_add_f32_e32 v21, 1.0, v21
	v_mul_f32_e32 v18, v30, v18
	v_add_f32_e32 v22, 1.0, v22
	v_mul_f32_e32 v19, v31, v19
	v_add_f32_e32 v23, 1.0, v23
	s_waitcnt vmcnt(0)
	v_fma_f32 v16, v16, v20, v24
	v_fma_f32 v17, v17, v21, v25
	v_fma_f32 v18, v18, v22, v26
	v_fmac_f32_e32 v27, v19, v23
	v_cvt_pk_bf16_f32 v16, v16, v17
	v_cvt_pk_bf16_f32 v17, v18, v27
	global_store_dwordx2 v[44:45], v[16:17], off offset:1536
	s_cbranch_scc0 .LBB0_15

.Ldpg_skip:
	s_cmpk_lg_u32 s36, 0x100
	s_cbranch_scc1 .Ldp1_skip
	s_cmpk_lt_u32 s57, 0xa0
	s_cbranch_scc1 .Ldp1_skip
	v_readlane_b32 s10, v254, 62
	s_nop 3
	s_cmp_lg_u32 s10, 0
	s_cbranch_scc1 .Ldp1_skip
	v_mov_b32_e32 v0, v167
	v_readlane_b32 s9, v251, 14
	v_readfirstlane_b32 s8, v0
	s_ashr_i32 s8, s8, 6
	s_add_i32 s8, s8, s9
	s_add_i32 s8, s8, 0x1b00
	s_movk_i32 s18, 0x5fff
	s_mov_b32 s56, 0x800000
	v_readlane_b32 s58, v254, 37
	v_readlane_b32 s59, v254, 38
	v_cmp_lt_i32_e32 vcc, v188, v187
	v_and_b32_e32 v4, 63, v0
	v_readlane_b32 s84, v254, 4
	v_cndmask_b32_e32 v2, v185, v188, vcc
	v_cmp_lt_i32_e32 vcc, v189, v187
	v_lshlrev_b32_e32 v6, 2, v2
	v_lshlrev_b32_e32 v156, 4, v4
	v_cndmask_b32_e32 v2, v185, v189, vcc
	v_cmp_lt_i32_e32 vcc, v190, v187
	v_lshlrev_b32_e32 v7, 2, v2
	v_readlane_b32 s85, v254, 5
	v_cndmask_b32_e32 v2, v185, v190, vcc
	v_cmp_lt_i32_e32 vcc, v191, v187
	s_waitcnt vmcnt(0)
	v_lshlrev_b32_e32 v8, 2, v2
	v_readlane_b32 s88, v254, 8
	v_cndmask_b32_e32 v2, v185, v191, vcc
	v_cmp_lt_i32_e32 vcc, v250, v187
	v_lshlrev_b32_e32 v9, 2, v2
	v_readlane_b32 s89, v254, 9
	v_cndmask_b32_e32 v2, v185, v250, vcc
	v_cmp_lt_i32_e32 vcc, v184, v187
	v_lshlrev_b32_e32 v10, 2, v2
	v_lshlrev_b32_e32 v12, 2, v4
	v_cndmask_b32_e32 v2, v185, v184, vcc
	v_readlane_b32 s12, v251, 12
	s_waitcnt lgkmcnt(0)
	v_lshl_add_u64 v[0:1], s[84:85], 0, v[156:157]
	v_lshlrev_b32_e32 v11, 2, v2
	v_lshl_add_u64 v[2:3], s[88:89], 0, v[156:157]
	v_or_b32_e32 v14, 0x100, v12
	v_or_b32_e32 v16, 0x200, v12
	v_or_b32_e32 v18, 0x300, v12
	v_lshlrev_b32_e32 v156, 3, v4
	v_readlane_b32 s13, v251, 13
	v_lshlrev_b32_e32 v12, 2, v12
	v_lshlrev_b32_e32 v13, 2, v14
	v_lshl_add_u64 v[4:5], s[12:13], 0, v[156:157]
	v_lshlrev_b32_e32 v14, 2, v16
	v_lshlrev_b32_e32 v15, 2, v18
	v_readlane_b32 s86, v254, 6
	v_readlane_b32 s87, v254, 7
	v_readlane_b32 s90, v254, 10
	v_readlane_b32 s91, v254, 11
	v_readlane_b32 s92, v254, 12
	v_readlane_b32 s93, v254, 13
	v_readlane_b32 s94, v254, 14
	v_readlane_b32 s95, v254, 15
	v_readlane_b32 s96, v254, 16
	v_readlane_b32 s97, v254, 17
	v_readlane_b32 s98, v254, 18
	v_readlane_b32 s99, v254, 19
	s_ashr_i32 s9, s8, 31
	s_lshl_b64 s[12:13], s[8:9], 12
	v_lshl_add_u64 v[124:125], v[0:1], 0, s[12:13]
	global_load_dwordx4 v[60:63], v[124:125], off
	global_load_dwordx4 v[64:67], v[124:125], off offset:1024
	global_load_dwordx4 v[68:71], v[124:125], off offset:2048
	global_load_dwordx4 v[72:75], v[124:125], off offset:3072
	global_load_dwordx4 v[108:111], v[2:3], off
	global_load_dwordx4 v[112:115], v[2:3], off offset:1024
	global_load_dwordx4 v[116:119], v[2:3], off offset:2048
	global_load_dwordx4 v[120:123], v[2:3], off offset:3072
